# P1/P4 tile epilogue stores with nt (streaming hint)
# baseline (speedup 1.0000x reference)
.LBB0_134:
	v_readlane_b32 s18, v254, 41
	v_lshl_add_u32 v151, s8, 8, v145
	v_lshl_or_b32 v152, s41, 8, v147
	v_readlane_b32 s19, v254, 42
	v_ashrrev_i32_e32 v153, 31, v152
	v_cvt_pk_bf16_f32 v68, v68, v69
	v_mov_b64_e32 v[154:155], s[18:19]
	v_cvt_pk_bf16_f32 v69, v70, v71
	v_cvt_pk_bf16_f32 v70, v64, v65
	v_add_u32_e32 v64, 0x80, v151
	v_mad_i64_i32 v[156:157], s[18:19], v151, s40, v[154:155]
	v_lshlrev_b64 v[152:153], 1, v[152:153]
	v_cvt_pk_bf16_f32 v108, v108, v109
	v_cvt_pk_bf16_f32 v109, v110, v111
	v_cvt_pk_bf16_f32 v110, v104, v105
	v_or_b32_e32 v104, 16, v151
	v_mad_i64_i32 v[64:65], s[18:19], v64, s40, v[154:155]
	v_cvt_pk_bf16_f32 v44, v44, v45
	v_cvt_pk_bf16_f32 v45, v46, v47
	v_cvt_pk_bf16_f32 v46, v40, v41
	v_add_u32_e32 v40, 0x90, v151
	v_lshl_add_u64 v[156:157], v[156:157], 0, v[152:153]
	v_cvt_pk_bf16_f32 v111, v106, v107
	v_mad_i64_i32 v[104:105], s[18:19], v104, s40, v[154:155]
	v_cvt_pk_bf16_f32 v92, v92, v93
	v_cvt_pk_bf16_f32 v93, v94, v95
	v_cvt_pk_bf16_f32 v94, v88, v89
	v_or_b32_e32 v88, 32, v151
	v_lshl_add_u64 v[64:65], v[64:65], 0, v[152:153]
	v_cvt_pk_bf16_f32 v47, v42, v43
	v_mad_i64_i32 v[40:41], s[18:19], v40, s40, v[154:155]
	v_cvt_pk_bf16_f32 v28, v28, v29
	v_cvt_pk_bf16_f32 v29, v30, v31
	v_cvt_pk_bf16_f32 v30, v24, v25
	v_add_u32_e32 v24, 0xa0, v151
	global_store_dwordx4 v[156:157], v[108:111], off offset:256 nt
	v_cvt_pk_bf16_f32 v95, v90, v91
	v_mad_i64_i32 v[88:89], s[18:19], v88, s40, v[154:155]
	v_lshl_add_u64 v[108:109], v[104:105], 0, v[152:153]
	v_cvt_pk_bf16_f32 v76, v76, v77
	v_cvt_pk_bf16_f32 v77, v78, v79
	v_cvt_pk_bf16_f32 v78, v72, v73
	v_or_b32_e32 v72, 48, v151
	global_store_dwordx4 v[64:65], v[44:47], off offset:256 nt
	v_cvt_pk_bf16_f32 v31, v26, v27
	v_mad_i64_i32 v[24:25], s[18:19], v24, s40, v[154:155]
	v_lshl_add_u64 v[44:45], v[40:41], 0, v[152:153]
	v_cvt_pk_bf16_f32 v12, v12, v13
	v_cvt_pk_bf16_f32 v13, v14, v15
	v_cvt_pk_bf16_f32 v14, v8, v9
	v_add_u32_e32 v8, 0xb0, v151
	global_store_dwordx4 v[108:109], v[92:95], off offset:256 nt
	v_cvt_pk_bf16_f32 v79, v74, v75
	v_mad_i64_i32 v[72:73], s[18:19], v72, s40, v[154:155]
	v_lshl_add_u64 v[92:93], v[88:89], 0, v[152:153]
	global_store_dwordx4 v[44:45], v[28:31], off offset:256 nt
	v_cvt_pk_bf16_f32 v15, v10, v11
	v_mad_i64_i32 v[8:9], s[18:19], v8, s40, v[154:155]
	v_lshl_add_u64 v[28:29], v[24:25], 0, v[152:153]
	v_cvt_pk_bf16_f32 v124, v124, v125
	v_cvt_pk_bf16_f32 v125, v126, v127
	v_cvt_pk_bf16_f32 v126, v120, v121
	v_cvt_pk_bf16_f32 v127, v122, v123
	v_cvt_pk_bf16_f32 v104, v116, v117
	v_cvt_pk_bf16_f32 v105, v118, v119
	v_cvt_pk_bf16_f32 v106, v112, v113
	v_cvt_pk_bf16_f32 v107, v114, v115
	v_cvt_pk_bf16_f32 v88, v100, v101
	v_cvt_pk_bf16_f32 v89, v102, v103
	v_cvt_pk_bf16_f32 v90, v96, v97
	v_cvt_pk_bf16_f32 v91, v98, v99
	global_store_dwordx4 v[92:93], v[76:79], off offset:256 nt
	v_cvt_pk_bf16_f32 v74, v80, v81
	v_cvt_pk_bf16_f32 v75, v82, v83
	v_lshl_add_u64 v[76:77], v[72:73], 0, v[152:153]
	v_cvt_pk_bf16_f32 v72, v84, v85
	v_cvt_pk_bf16_f32 v73, v86, v87
	v_cvt_pk_bf16_f32 v71, v66, v67
	v_cvt_pk_bf16_f32 v60, v60, v61
	v_cvt_pk_bf16_f32 v61, v62, v63
	v_cvt_pk_bf16_f32 v62, v56, v57
	v_cvt_pk_bf16_f32 v63, v58, v59
	v_cvt_pk_bf16_f32 v40, v52, v53
	v_cvt_pk_bf16_f32 v41, v54, v55
	v_cvt_pk_bf16_f32 v42, v48, v49
	v_cvt_pk_bf16_f32 v43, v50, v51
	v_cvt_pk_bf16_f32 v24, v36, v37
	v_cvt_pk_bf16_f32 v25, v38, v39
	v_cvt_pk_bf16_f32 v26, v32, v33
	v_cvt_pk_bf16_f32 v27, v34, v35
	global_store_dwordx4 v[28:29], v[12:15], off offset:256 nt
	v_cvt_pk_bf16_f32 v10, v16, v17
	v_cvt_pk_bf16_f32 v11, v18, v19
	v_lshl_add_u64 v[12:13], v[8:9], 0, v[152:153]
	v_cvt_pk_bf16_f32 v8, v20, v21
	v_cvt_pk_bf16_f32 v9, v22, v23
	v_cvt_pk_bf16_f32 v4, v4, v5
	v_cvt_pk_bf16_f32 v5, v6, v7
	v_cvt_pk_bf16_f32 v6, v0, v1
	v_cvt_pk_bf16_f32 v7, v2, v3
	s_andn2_b64 vcc, exec, s[0:1]
	s_mov_b64 s[0:1], -1
	global_store_dwordx4 v[156:157], v[124:127], off nt
	global_store_dwordx4 v[108:109], v[104:107], off nt
	global_store_dwordx4 v[92:93], v[88:91], off nt
	global_store_dwordx4 v[76:77], v[72:75], off nt
	global_store_dwordx4 v[76:77], v[68:71], off offset:256 nt
	global_store_dwordx4 v[64:65], v[60:63], off nt
	global_store_dwordx4 v[44:45], v[40:43], off nt
	global_store_dwordx4 v[28:29], v[24:27], off nt
	global_store_dwordx4 v[12:13], v[8:11], off nt
	global_store_dwordx4 v[12:13], v[4:7], off offset:256 nt
	s_cbranch_vccnz .LBB0_127
	s_andn2_b64 vcc, exec, s[2:3]
	s_cbranch_vccnz .LBB0_126
	s_barrier
	s_branch .LBB0_126

.LBB0_503:
	v_max_f32_e32 v120, v120, v120
	v_max_f32_e32 v121, v121, v121
	v_max_f32_e32 v120, 0, v120
	v_max_f32_e32 v121, 0, v121
	s_waitcnt vmcnt(0)
	v_mul_f32_e32 v158, v175, v175
	v_pk_mul_f32 v[120:121], v[120:121], v[120:121]
	v_max_f32_e32 v124, v124, v124
	v_pk_mul_f32 v[160:161], v[158:159], v[120:121] op_sel_hi:[0,1]
	v_max_f32_e32 v121, v122, v122
	v_max_f32_e32 v120, v126, v126
	v_max_f32_e32 v122, 0, v121
	v_max_f32_e32 v121, v127, v127
	v_max_f32_e32 v125, v125, v125
	v_max_f32_e32 v120, 0, v120
	v_max_f32_e32 v121, 0, v121
	v_max_f32_e32 v123, v123, v123
	v_lshl_or_b32 v154, s48, 8, v166
	v_readlane_b32 s26, v254, 39
	v_max_f32_e32 v124, 0, v124
	v_max_f32_e32 v125, 0, v125
	v_max_f32_e32 v123, 0, v123
	v_pk_mul_f32 v[120:121], v[120:121], v[120:121]
	v_ashrrev_i32_e32 v155, 31, v154
	v_lshlrev_b64 v[156:157], 13, v[152:153]
	v_readlane_b32 s27, v254, 40
	v_pk_mul_f32 v[124:125], v[124:125], v[124:125]
	v_pk_mul_f32 v[126:127], v[158:159], v[120:121] op_sel_hi:[0,1]
	v_pk_mul_f32 v[120:121], v[122:123], v[122:123]
	v_max_f32_e32 v112, v112, v112
	v_max_f32_e32 v113, v113, v113
	v_lshl_add_u64 v[156:157], s[26:27], 0, v[156:157]
	v_lshlrev_b64 v[154:155], 1, v[154:155]
	v_pk_mul_f32 v[124:125], v[158:159], v[124:125] op_sel_hi:[0,1]
	v_pk_mul_f32 v[162:163], v[158:159], v[120:121] op_sel_hi:[0,1]
	v_max_f32_e32 v112, 0, v112
	v_max_f32_e32 v113, 0, v113
	v_lshl_add_u64 v[156:157], v[156:157], 0, v[154:155]
	v_cvt_pk_bf16_f32 v120, v124, v125
	v_cvt_pk_bf16_f32 v121, v126, v127
	v_cvt_pk_bf16_f32 v122, v160, v161
	v_cvt_pk_bf16_f32 v123, v162, v163
	v_pk_mul_f32 v[112:113], v[112:113], v[112:113]
	global_store_dwordx4 v[156:157], v[120:123], off nt
	v_max_f32_e32 v116, v116, v116
	v_max_f32_e32 v117, v117, v117
	v_pk_mul_f32 v[120:121], v[158:159], v[112:113] op_sel_hi:[0,1]
	v_max_f32_e32 v113, v114, v114
	v_max_f32_e32 v112, v118, v118
	v_max_f32_e32 v114, 0, v113
	v_max_f32_e32 v113, v119, v119
	v_max_f32_e32 v112, 0, v112
	v_max_f32_e32 v113, 0, v113
	v_max_f32_e32 v115, v115, v115
	v_max_f32_e32 v116, 0, v116
	v_max_f32_e32 v117, 0, v117
	v_max_f32_e32 v115, 0, v115
	v_pk_mul_f32 v[112:113], v[112:113], v[112:113]
	v_pk_mul_f32 v[116:117], v[116:117], v[116:117]
	v_pk_mul_f32 v[118:119], v[158:159], v[112:113] op_sel_hi:[0,1]
	v_pk_mul_f32 v[112:113], v[114:115], v[114:115]
	v_pk_mul_f32 v[116:117], v[158:159], v[116:117] op_sel_hi:[0,1]
	v_pk_mul_f32 v[122:123], v[158:159], v[112:113] op_sel_hi:[0,1]
	v_max_f32_e32 v104, v104, v104
	v_max_f32_e32 v105, v105, v105
	v_cvt_pk_bf16_f32 v112, v116, v117
	v_cvt_pk_bf16_f32 v113, v118, v119
	v_cvt_pk_bf16_f32 v114, v120, v121
	v_cvt_pk_bf16_f32 v115, v122, v123
	v_max_f32_e32 v104, 0, v104
	v_max_f32_e32 v105, 0, v105
	global_store_dwordx4 v[156:157], v[112:115], off offset:256 nt
	v_pk_mul_f32 v[104:105], v[104:105], v[104:105]
	v_max_f32_e32 v108, v108, v108
	v_mul_f32_e32 v114, v174, v174
	v_pk_mul_f32 v[116:117], v[114:115], v[104:105] op_sel_hi:[0,1]
	v_max_f32_e32 v105, v106, v106
	v_max_f32_e32 v104, v110, v110
	v_max_f32_e32 v106, 0, v105
	v_max_f32_e32 v105, v111, v111
	v_or_b32_e32 v112, 16, v152
	v_max_f32_e32 v109, v109, v109
	v_max_f32_e32 v104, 0, v104
	v_max_f32_e32 v105, 0, v105
	v_max_f32_e32 v107, v107, v107
	v_ashrrev_i32_e32 v113, 31, v112
	v_max_f32_e32 v108, 0, v108
	v_max_f32_e32 v109, 0, v109
	v_max_f32_e32 v107, 0, v107
	v_pk_mul_f32 v[104:105], v[104:105], v[104:105]
	v_lshlrev_b64 v[112:113], 13, v[112:113]
	v_pk_mul_f32 v[108:109], v[108:109], v[108:109]
	v_pk_mul_f32 v[110:111], v[114:115], v[104:105] op_sel_hi:[0,1]
	v_pk_mul_f32 v[104:105], v[106:107], v[106:107]
	v_max_f32_e32 v96, v96, v96
	v_max_f32_e32 v97, v97, v97
	v_lshl_add_u64 v[112:113], s[26:27], 0, v[112:113]
	v_pk_mul_f32 v[108:109], v[114:115], v[108:109] op_sel_hi:[0,1]
	v_pk_mul_f32 v[118:119], v[114:115], v[104:105] op_sel_hi:[0,1]
	v_max_f32_e32 v96, 0, v96
	v_max_f32_e32 v97, 0, v97
	v_lshl_add_u64 v[112:113], v[112:113], 0, v[154:155]
	v_cvt_pk_bf16_f32 v104, v108, v109
	v_cvt_pk_bf16_f32 v105, v110, v111
	v_cvt_pk_bf16_f32 v106, v116, v117
	v_cvt_pk_bf16_f32 v107, v118, v119
	v_pk_mul_f32 v[96:97], v[96:97], v[96:97]
	global_store_dwordx4 v[112:113], v[104:107], off nt
	v_max_f32_e32 v100, v100, v100
	v_max_f32_e32 v101, v101, v101
	v_pk_mul_f32 v[104:105], v[114:115], v[96:97] op_sel_hi:[0,1]
	v_max_f32_e32 v97, v98, v98
	v_max_f32_e32 v96, v102, v102
	v_max_f32_e32 v98, 0, v97
	v_max_f32_e32 v97, v103, v103
	v_max_f32_e32 v96, 0, v96
	v_max_f32_e32 v97, 0, v97
	v_max_f32_e32 v99, v99, v99
	v_max_f32_e32 v100, 0, v100
	v_max_f32_e32 v101, 0, v101
	v_max_f32_e32 v99, 0, v99
	v_pk_mul_f32 v[96:97], v[96:97], v[96:97]
	v_pk_mul_f32 v[100:101], v[100:101], v[100:101]
	v_pk_mul_f32 v[102:103], v[114:115], v[96:97] op_sel_hi:[0,1]
	v_pk_mul_f32 v[96:97], v[98:99], v[98:99]
	v_pk_mul_f32 v[100:101], v[114:115], v[100:101] op_sel_hi:[0,1]
	v_pk_mul_f32 v[106:107], v[114:115], v[96:97] op_sel_hi:[0,1]
	v_max_f32_e32 v88, v88, v88
	v_max_f32_e32 v89, v89, v89
	v_cvt_pk_bf16_f32 v96, v100, v101
	v_cvt_pk_bf16_f32 v97, v102, v103
	v_cvt_pk_bf16_f32 v98, v104, v105
	v_cvt_pk_bf16_f32 v99, v106, v107
	v_max_f32_e32 v88, 0, v88
	v_max_f32_e32 v89, 0, v89
	global_store_dwordx4 v[112:113], v[96:99], off offset:256 nt
	v_pk_mul_f32 v[88:89], v[88:89], v[88:89]
	v_max_f32_e32 v92, v92, v92
	v_mul_f32_e32 v98, v173, v173
	v_pk_mul_f32 v[100:101], v[98:99], v[88:89] op_sel_hi:[0,1]
	v_max_f32_e32 v89, v90, v90
	v_max_f32_e32 v88, v94, v94
	v_max_f32_e32 v90, 0, v89
	v_max_f32_e32 v89, v95, v95
	v_or_b32_e32 v96, 32, v152
	v_max_f32_e32 v93, v93, v93
	v_max_f32_e32 v88, 0, v88
	v_max_f32_e32 v89, 0, v89
	v_max_f32_e32 v91, v91, v91
	v_ashrrev_i32_e32 v97, 31, v96
	v_max_f32_e32 v92, 0, v92
	v_max_f32_e32 v93, 0, v93
	v_max_f32_e32 v91, 0, v91
	v_pk_mul_f32 v[88:89], v[88:89], v[88:89]
	v_lshlrev_b64 v[96:97], 13, v[96:97]
	v_pk_mul_f32 v[92:93], v[92:93], v[92:93]
	v_pk_mul_f32 v[94:95], v[98:99], v[88:89] op_sel_hi:[0,1]
	v_pk_mul_f32 v[88:89], v[90:91], v[90:91]
	v_max_f32_e32 v80, v80, v80
	v_max_f32_e32 v81, v81, v81
	v_lshl_add_u64 v[96:97], s[26:27], 0, v[96:97]
	v_pk_mul_f32 v[92:93], v[98:99], v[92:93] op_sel_hi:[0,1]
	v_pk_mul_f32 v[102:103], v[98:99], v[88:89] op_sel_hi:[0,1]
	v_max_f32_e32 v80, 0, v80
	v_max_f32_e32 v81, 0, v81
	v_lshl_add_u64 v[96:97], v[96:97], 0, v[154:155]
	v_cvt_pk_bf16_f32 v88, v92, v93
	v_cvt_pk_bf16_f32 v89, v94, v95
	v_cvt_pk_bf16_f32 v90, v100, v101
	v_cvt_pk_bf16_f32 v91, v102, v103
	v_pk_mul_f32 v[80:81], v[80:81], v[80:81]
	global_store_dwordx4 v[96:97], v[88:91], off nt
	v_max_f32_e32 v84, v84, v84
	v_max_f32_e32 v85, v85, v85
	v_pk_mul_f32 v[88:89], v[98:99], v[80:81] op_sel_hi:[0,1]
	v_max_f32_e32 v81, v82, v82
	v_max_f32_e32 v80, v86, v86
	v_max_f32_e32 v82, 0, v81
	v_max_f32_e32 v81, v87, v87
	v_max_f32_e32 v80, 0, v80
	v_max_f32_e32 v81, 0, v81
	v_max_f32_e32 v83, v83, v83
	v_max_f32_e32 v84, 0, v84
	v_max_f32_e32 v85, 0, v85
	v_max_f32_e32 v83, 0, v83
	v_pk_mul_f32 v[80:81], v[80:81], v[80:81]
	v_pk_mul_f32 v[84:85], v[84:85], v[84:85]
	v_pk_mul_f32 v[86:87], v[98:99], v[80:81] op_sel_hi:[0,1]
	v_pk_mul_f32 v[80:81], v[82:83], v[82:83]
	v_pk_mul_f32 v[84:85], v[98:99], v[84:85] op_sel_hi:[0,1]
	v_pk_mul_f32 v[90:91], v[98:99], v[80:81] op_sel_hi:[0,1]
	v_max_f32_e32 v72, v72, v72
	v_max_f32_e32 v73, v73, v73
	v_cvt_pk_bf16_f32 v80, v84, v85
	v_cvt_pk_bf16_f32 v81, v86, v87
	v_cvt_pk_bf16_f32 v82, v88, v89
	v_cvt_pk_bf16_f32 v83, v90, v91
	v_max_f32_e32 v72, 0, v72
	v_max_f32_e32 v73, 0, v73
	global_store_dwordx4 v[96:97], v[80:83], off offset:256 nt
	v_pk_mul_f32 v[72:73], v[72:73], v[72:73]
	v_max_f32_e32 v76, v76, v76
	v_mul_f32_e32 v82, v172, v172
	v_pk_mul_f32 v[84:85], v[82:83], v[72:73] op_sel_hi:[0,1]
	v_max_f32_e32 v73, v74, v74
	v_max_f32_e32 v72, v78, v78
	v_max_f32_e32 v74, 0, v73
	v_max_f32_e32 v73, v79, v79
	v_or_b32_e32 v80, 48, v152
	v_max_f32_e32 v77, v77, v77
	v_max_f32_e32 v72, 0, v72
	v_max_f32_e32 v73, 0, v73
	v_max_f32_e32 v75, v75, v75
	v_ashrrev_i32_e32 v81, 31, v80
	v_max_f32_e32 v76, 0, v76
	v_max_f32_e32 v77, 0, v77
	v_max_f32_e32 v75, 0, v75
	v_pk_mul_f32 v[72:73], v[72:73], v[72:73]
	v_lshlrev_b64 v[80:81], 13, v[80:81]
	v_pk_mul_f32 v[76:77], v[76:77], v[76:77]
	v_pk_mul_f32 v[78:79], v[82:83], v[72:73] op_sel_hi:[0,1]
	v_pk_mul_f32 v[72:73], v[74:75], v[74:75]
	v_max_f32_e32 v64, v64, v64
	v_max_f32_e32 v65, v65, v65
	v_lshl_add_u64 v[80:81], s[26:27], 0, v[80:81]
	v_pk_mul_f32 v[76:77], v[82:83], v[76:77] op_sel_hi:[0,1]
	v_pk_mul_f32 v[86:87], v[82:83], v[72:73] op_sel_hi:[0,1]
	v_max_f32_e32 v64, 0, v64
	v_max_f32_e32 v65, 0, v65
	v_lshl_add_u64 v[80:81], v[80:81], 0, v[154:155]
	v_cvt_pk_bf16_f32 v72, v76, v77
	v_cvt_pk_bf16_f32 v73, v78, v79
	v_cvt_pk_bf16_f32 v74, v84, v85
	v_cvt_pk_bf16_f32 v75, v86, v87
	v_pk_mul_f32 v[64:65], v[64:65], v[64:65]
	global_store_dwordx4 v[80:81], v[72:75], off nt
	v_max_f32_e32 v68, v68, v68
	v_max_f32_e32 v69, v69, v69
	v_pk_mul_f32 v[72:73], v[82:83], v[64:65] op_sel_hi:[0,1]
	v_max_f32_e32 v65, v66, v66
	v_max_f32_e32 v64, v70, v70
	v_max_f32_e32 v66, 0, v65
	v_max_f32_e32 v65, v71, v71
	v_max_f32_e32 v64, 0, v64
	v_max_f32_e32 v65, 0, v65
	v_max_f32_e32 v67, v67, v67
	v_max_f32_e32 v68, 0, v68
	v_max_f32_e32 v69, 0, v69
	v_max_f32_e32 v67, 0, v67
	v_pk_mul_f32 v[64:65], v[64:65], v[64:65]
	v_pk_mul_f32 v[68:69], v[68:69], v[68:69]
	v_pk_mul_f32 v[70:71], v[82:83], v[64:65] op_sel_hi:[0,1]
	v_pk_mul_f32 v[64:65], v[66:67], v[66:67]
	v_pk_mul_f32 v[68:69], v[82:83], v[68:69] op_sel_hi:[0,1]
	v_pk_mul_f32 v[74:75], v[82:83], v[64:65] op_sel_hi:[0,1]
	v_max_f32_e32 v56, v56, v56
	v_max_f32_e32 v57, v57, v57
	v_cvt_pk_bf16_f32 v64, v68, v69
	v_cvt_pk_bf16_f32 v65, v70, v71
	v_cvt_pk_bf16_f32 v66, v72, v73
	v_cvt_pk_bf16_f32 v67, v74, v75
	v_max_f32_e32 v56, 0, v56
	v_max_f32_e32 v57, 0, v57
	global_store_dwordx4 v[80:81], v[64:67], off offset:256 nt
	v_pk_mul_f32 v[56:57], v[56:57], v[56:57]
	v_max_f32_e32 v60, v60, v60
	v_mul_f32_e32 v66, v171, v171
	v_pk_mul_f32 v[68:69], v[66:67], v[56:57] op_sel_hi:[0,1]
	v_max_f32_e32 v57, v58, v58
	v_max_f32_e32 v56, v62, v62
	v_max_f32_e32 v58, 0, v57
	v_max_f32_e32 v57, v63, v63
	v_max_f32_e32 v61, v61, v61
	v_max_f32_e32 v56, 0, v56
	v_max_f32_e32 v57, 0, v57
	v_max_f32_e32 v59, v59, v59
	v_max_f32_e32 v60, 0, v60
	v_max_f32_e32 v61, 0, v61
	v_max_f32_e32 v59, 0, v59
	v_pk_mul_f32 v[56:57], v[56:57], v[56:57]
	v_lshlrev_b64 v[64:65], 13, v[150:151]
	v_pk_mul_f32 v[60:61], v[60:61], v[60:61]
	v_pk_mul_f32 v[62:63], v[66:67], v[56:57] op_sel_hi:[0,1]
	v_pk_mul_f32 v[56:57], v[58:59], v[58:59]
	v_max_f32_e32 v48, v48, v48
	v_max_f32_e32 v49, v49, v49
	v_lshl_add_u64 v[64:65], s[26:27], 0, v[64:65]
	v_pk_mul_f32 v[60:61], v[66:67], v[60:61] op_sel_hi:[0,1]
	v_pk_mul_f32 v[70:71], v[66:67], v[56:57] op_sel_hi:[0,1]
	v_max_f32_e32 v48, 0, v48
	v_max_f32_e32 v49, 0, v49
	v_lshl_add_u64 v[64:65], v[64:65], 0, v[154:155]
	v_cvt_pk_bf16_f32 v56, v60, v61
	v_cvt_pk_bf16_f32 v57, v62, v63
	v_cvt_pk_bf16_f32 v58, v68, v69
	v_cvt_pk_bf16_f32 v59, v70, v71
	v_pk_mul_f32 v[48:49], v[48:49], v[48:49]
	global_store_dwordx4 v[64:65], v[56:59], off nt
	v_max_f32_e32 v52, v52, v52
	v_max_f32_e32 v53, v53, v53
	v_pk_mul_f32 v[56:57], v[66:67], v[48:49] op_sel_hi:[0,1]
	v_max_f32_e32 v49, v50, v50
	v_max_f32_e32 v48, v54, v54
	v_max_f32_e32 v50, 0, v49
	v_max_f32_e32 v49, v55, v55
	v_max_f32_e32 v48, 0, v48
	v_max_f32_e32 v49, 0, v49
	v_max_f32_e32 v51, v51, v51
	v_max_f32_e32 v52, 0, v52
	v_max_f32_e32 v53, 0, v53
	v_max_f32_e32 v51, 0, v51
	v_pk_mul_f32 v[48:49], v[48:49], v[48:49]
	v_pk_mul_f32 v[52:53], v[52:53], v[52:53]
	v_pk_mul_f32 v[54:55], v[66:67], v[48:49] op_sel_hi:[0,1]
	v_pk_mul_f32 v[48:49], v[50:51], v[50:51]
	v_pk_mul_f32 v[52:53], v[66:67], v[52:53] op_sel_hi:[0,1]
	v_pk_mul_f32 v[58:59], v[66:67], v[48:49] op_sel_hi:[0,1]
	v_max_f32_e32 v40, v40, v40
	v_max_f32_e32 v41, v41, v41
	v_cvt_pk_bf16_f32 v48, v52, v53
	v_cvt_pk_bf16_f32 v49, v54, v55
	v_cvt_pk_bf16_f32 v50, v56, v57
	v_cvt_pk_bf16_f32 v51, v58, v59
	v_max_f32_e32 v40, 0, v40
	v_max_f32_e32 v41, 0, v41
	global_store_dwordx4 v[64:65], v[48:51], off offset:256 nt
	v_pk_mul_f32 v[40:41], v[40:41], v[40:41]
	v_max_f32_e32 v44, v44, v44
	v_mul_f32_e32 v50, v170, v170
	v_pk_mul_f32 v[52:53], v[50:51], v[40:41] op_sel_hi:[0,1]
	v_max_f32_e32 v41, v42, v42
	v_max_f32_e32 v40, v46, v46
	v_max_f32_e32 v42, 0, v41
	v_max_f32_e32 v41, v47, v47
	v_max_f32_e32 v45, v45, v45
	v_max_f32_e32 v40, 0, v40
	v_max_f32_e32 v41, 0, v41
	v_max_f32_e32 v43, v43, v43
	v_max_f32_e32 v44, 0, v44
	v_max_f32_e32 v45, 0, v45
	v_max_f32_e32 v43, 0, v43
	v_pk_mul_f32 v[40:41], v[40:41], v[40:41]
	v_lshlrev_b64 v[48:49], 13, v[148:149]
	v_pk_mul_f32 v[44:45], v[44:45], v[44:45]
	v_pk_mul_f32 v[46:47], v[50:51], v[40:41] op_sel_hi:[0,1]
	v_pk_mul_f32 v[40:41], v[42:43], v[42:43]
	v_max_f32_e32 v32, v32, v32
	v_max_f32_e32 v33, v33, v33
	v_lshl_add_u64 v[48:49], s[26:27], 0, v[48:49]
	v_pk_mul_f32 v[44:45], v[50:51], v[44:45] op_sel_hi:[0,1]
	v_pk_mul_f32 v[54:55], v[50:51], v[40:41] op_sel_hi:[0,1]
	v_max_f32_e32 v32, 0, v32
	v_max_f32_e32 v33, 0, v33
	v_lshl_add_u64 v[48:49], v[48:49], 0, v[154:155]
	v_cvt_pk_bf16_f32 v40, v44, v45
	v_cvt_pk_bf16_f32 v41, v46, v47
	v_cvt_pk_bf16_f32 v42, v52, v53
	v_cvt_pk_bf16_f32 v43, v54, v55
	v_pk_mul_f32 v[32:33], v[32:33], v[32:33]
	global_store_dwordx4 v[48:49], v[40:43], off nt
	v_max_f32_e32 v36, v36, v36
	v_max_f32_e32 v37, v37, v37
	v_pk_mul_f32 v[40:41], v[50:51], v[32:33] op_sel_hi:[0,1]
	v_max_f32_e32 v33, v34, v34
	v_max_f32_e32 v32, v38, v38
	v_max_f32_e32 v34, 0, v33
	v_max_f32_e32 v33, v39, v39
	v_max_f32_e32 v32, 0, v32
	v_max_f32_e32 v33, 0, v33
	v_max_f32_e32 v35, v35, v35
	v_max_f32_e32 v36, 0, v36
	v_max_f32_e32 v37, 0, v37
	v_max_f32_e32 v35, 0, v35
	v_pk_mul_f32 v[32:33], v[32:33], v[32:33]
	v_pk_mul_f32 v[36:37], v[36:37], v[36:37]
	v_pk_mul_f32 v[38:39], v[50:51], v[32:33] op_sel_hi:[0,1]
	v_pk_mul_f32 v[32:33], v[34:35], v[34:35]
	v_pk_mul_f32 v[36:37], v[50:51], v[36:37] op_sel_hi:[0,1]
	v_pk_mul_f32 v[42:43], v[50:51], v[32:33] op_sel_hi:[0,1]
	v_max_f32_e32 v24, v24, v24
	v_max_f32_e32 v25, v25, v25
	v_cvt_pk_bf16_f32 v32, v36, v37
	v_cvt_pk_bf16_f32 v33, v38, v39
	v_cvt_pk_bf16_f32 v34, v40, v41
	v_cvt_pk_bf16_f32 v35, v42, v43
	v_max_f32_e32 v24, 0, v24
	v_max_f32_e32 v25, 0, v25
	global_store_dwordx4 v[48:49], v[32:35], off offset:256 nt
	v_pk_mul_f32 v[24:25], v[24:25], v[24:25]
	v_max_f32_e32 v28, v28, v28
	v_mul_f32_e32 v34, v169, v169
	v_pk_mul_f32 v[36:37], v[34:35], v[24:25] op_sel_hi:[0,1]
	v_max_f32_e32 v25, v26, v26
	v_max_f32_e32 v24, v30, v30
	v_max_f32_e32 v26, 0, v25
	v_max_f32_e32 v25, v31, v31
	v_max_f32_e32 v29, v29, v29
	v_max_f32_e32 v24, 0, v24
	v_max_f32_e32 v25, 0, v25
	v_max_f32_e32 v27, v27, v27
	v_max_f32_e32 v28, 0, v28
	v_max_f32_e32 v29, 0, v29
	v_max_f32_e32 v27, 0, v27
	v_pk_mul_f32 v[24:25], v[24:25], v[24:25]
	v_lshlrev_b64 v[32:33], 13, v[146:147]
	v_pk_mul_f32 v[28:29], v[28:29], v[28:29]
	v_pk_mul_f32 v[30:31], v[34:35], v[24:25] op_sel_hi:[0,1]
	v_pk_mul_f32 v[24:25], v[26:27], v[26:27]
	v_max_f32_e32 v16, v16, v16
	v_max_f32_e32 v17, v17, v17
	v_lshl_add_u64 v[32:33], s[26:27], 0, v[32:33]
	v_pk_mul_f32 v[28:29], v[34:35], v[28:29] op_sel_hi:[0,1]
	v_pk_mul_f32 v[38:39], v[34:35], v[24:25] op_sel_hi:[0,1]
	v_max_f32_e32 v16, 0, v16
	v_max_f32_e32 v17, 0, v17
	v_lshl_add_u64 v[32:33], v[32:33], 0, v[154:155]
	v_cvt_pk_bf16_f32 v24, v28, v29
	v_cvt_pk_bf16_f32 v25, v30, v31
	v_cvt_pk_bf16_f32 v26, v36, v37
	v_cvt_pk_bf16_f32 v27, v38, v39
	v_pk_mul_f32 v[16:17], v[16:17], v[16:17]
	global_store_dwordx4 v[32:33], v[24:27], off nt
	v_max_f32_e32 v20, v20, v20
	v_max_f32_e32 v21, v21, v21
	v_pk_mul_f32 v[24:25], v[34:35], v[16:17] op_sel_hi:[0,1]
	v_max_f32_e32 v17, v18, v18
	v_max_f32_e32 v16, v22, v22
	v_max_f32_e32 v18, 0, v17
	v_max_f32_e32 v17, v23, v23
	v_max_f32_e32 v16, 0, v16
	v_max_f32_e32 v17, 0, v17
	v_max_f32_e32 v19, v19, v19
	v_max_f32_e32 v20, 0, v20
	v_max_f32_e32 v21, 0, v21
	v_max_f32_e32 v19, 0, v19
	v_pk_mul_f32 v[16:17], v[16:17], v[16:17]
	v_pk_mul_f32 v[20:21], v[20:21], v[20:21]
	v_pk_mul_f32 v[22:23], v[34:35], v[16:17] op_sel_hi:[0,1]
	v_pk_mul_f32 v[16:17], v[18:19], v[18:19]
	v_pk_mul_f32 v[20:21], v[34:35], v[20:21] op_sel_hi:[0,1]
	v_pk_mul_f32 v[26:27], v[34:35], v[16:17] op_sel_hi:[0,1]
	v_max_f32_e32 v8, v8, v8
	v_max_f32_e32 v9, v9, v9
	v_cvt_pk_bf16_f32 v16, v20, v21
	v_cvt_pk_bf16_f32 v17, v22, v23
	v_cvt_pk_bf16_f32 v18, v24, v25
	v_cvt_pk_bf16_f32 v19, v26, v27
	v_max_f32_e32 v8, 0, v8
	v_max_f32_e32 v9, 0, v9
	global_store_dwordx4 v[32:33], v[16:19], off offset:256 nt
	v_pk_mul_f32 v[8:9], v[8:9], v[8:9]
	v_max_f32_e32 v12, v12, v12
	v_mul_f32_e32 v18, v168, v168
	v_pk_mul_f32 v[20:21], v[18:19], v[8:9] op_sel_hi:[0,1]
	v_max_f32_e32 v9, v10, v10
	v_max_f32_e32 v8, v14, v14
	v_max_f32_e32 v10, 0, v9
	v_max_f32_e32 v9, v15, v15
	v_max_f32_e32 v13, v13, v13
	v_max_f32_e32 v8, 0, v8
	v_max_f32_e32 v9, 0, v9
	v_max_f32_e32 v11, v11, v11
	v_max_f32_e32 v12, 0, v12
	v_max_f32_e32 v13, 0, v13
	v_max_f32_e32 v11, 0, v11
	v_pk_mul_f32 v[8:9], v[8:9], v[8:9]
	v_lshlrev_b64 v[16:17], 13, v[144:145]
	v_pk_mul_f32 v[12:13], v[12:13], v[12:13]
	v_pk_mul_f32 v[14:15], v[18:19], v[8:9] op_sel_hi:[0,1]
	v_pk_mul_f32 v[8:9], v[10:11], v[10:11]
	v_max_f32_e32 v0, v0, v0
	v_max_f32_e32 v1, v1, v1
	v_lshl_add_u64 v[16:17], s[26:27], 0, v[16:17]
	v_pk_mul_f32 v[12:13], v[18:19], v[12:13] op_sel_hi:[0,1]
	v_pk_mul_f32 v[22:23], v[18:19], v[8:9] op_sel_hi:[0,1]
	v_max_f32_e32 v0, 0, v0
	v_max_f32_e32 v1, 0, v1
	v_lshl_add_u64 v[16:17], v[16:17], 0, v[154:155]
	v_cvt_pk_bf16_f32 v8, v12, v13
	v_cvt_pk_bf16_f32 v9, v14, v15
	v_cvt_pk_bf16_f32 v10, v20, v21
	v_cvt_pk_bf16_f32 v11, v22, v23
	v_pk_mul_f32 v[0:1], v[0:1], v[0:1]
	global_store_dwordx4 v[16:17], v[8:11], off nt
	v_max_f32_e32 v4, v4, v4
	v_max_f32_e32 v5, v5, v5
	v_pk_mul_f32 v[8:9], v[18:19], v[0:1] op_sel_hi:[0,1]
	v_max_f32_e32 v1, v2, v2
	v_max_f32_e32 v0, v6, v6
	v_max_f32_e32 v2, 0, v1
	v_max_f32_e32 v1, v7, v7
	v_max_f32_e32 v0, 0, v0
	v_max_f32_e32 v1, 0, v1
	v_max_f32_e32 v3, v3, v3
	v_max_f32_e32 v4, 0, v4
	v_max_f32_e32 v5, 0, v5
	v_max_f32_e32 v3, 0, v3
	v_pk_mul_f32 v[0:1], v[0:1], v[0:1]
	v_pk_mul_f32 v[4:5], v[4:5], v[4:5]
	v_pk_mul_f32 v[6:7], v[18:19], v[0:1] op_sel_hi:[0,1]
	v_pk_mul_f32 v[0:1], v[2:3], v[2:3]
	v_pk_mul_f32 v[4:5], v[18:19], v[4:5] op_sel_hi:[0,1]
	v_pk_mul_f32 v[10:11], v[18:19], v[0:1] op_sel_hi:[0,1]
	v_cvt_pk_bf16_f32 v0, v4, v5
	v_cvt_pk_bf16_f32 v1, v6, v7
	v_cvt_pk_bf16_f32 v2, v8, v9
	v_cvt_pk_bf16_f32 v3, v10, v11
	s_andn2_b64 vcc, exec, s[0:1]
	s_mov_b64 s[0:1], -1
	global_store_dwordx4 v[16:17], v[0:3], off offset:256 nt
	s_cbranch_vccnz .LBB0_490
	s_andn2_b64 vcc, exec, s[2:3]
	s_cbranch_vccnz .LBB0_489
	s_barrier
	s_branch .LBB0_489
